# P6 H2 row stores made write-through (sc0 sc1): full-line streaming stores no longer pile up dirty in L2 for the end-of-phase writeback
# speedup vs baseline: 1.0053x; 1.0053x over previous
; __device__ __forceinline__ unsigned cvt_pk_bf16(float lo, float hi) { unsigned r; asm("v_cvt_pk_bf16_f32 %0, %1, %2" : "=v"(r) : "v"(lo), "v"(hi)); return r; }
; #define FRESH_IDS() const int tid = fresh_tid(), lane = tid & 63, wid = __builtin_amdgcn_readfirstlane(tid >> 6); (void)tid; (void)lane; (void)wid
; __device__ __forceinline__ void norm_load(const float* xrow, f32x4 (&v)[4], int lane) {
; #pragma unroll
;     for (int j = 0; j < 4; ++j) v[j] = __builtin_nontemporal_load((const f32x4*)xrow + lane + 64 * j);
; }
; __device__ __forceinline__ void norm_apply(const f32x4 (&v)[4], const float* g, const float* sc, const float* sh, bf16_t* orow, int lane) {
;     float s = 0.f;
; #pragma unroll
;     for (int j = 0; j < 4; ++j) s += (v[j][0] * v[j][0] + v[j][1] * v[j][1]) + (v[j][2] * v[j][2] + v[j][3] * v[j][3]);
;     const float rstd = rsqrtf(wave_sum(s) * (1.f / 1024.f) + EPS);
; #pragma unroll
;     for (int j = 0; j < 4; ++j) { const int c4 = lane + 64 * j;
;         const f32x4 gg = *((const f32x4*)g + c4), cc = *((const f32x4*)sc + c4), hh = *((const f32x4*)sh + c4);
;         const f32x4 h = v[j] * rstd * gg * (cc + 1.f) + hh;
;         u32x2 w; w.x = cvt_pk_bf16(h[0], h[1]); w.y = cvt_pk_bf16(h[2], h[3]);
;         *((u32x2*)orow + c4) = w; }
; }
; __global__ void __launch_bounds__(512, 2) mega_fwd(Args a) {
;     ...
;     { FRESH_IDS();
;         int row = bx * 8 + wid; f32x4 nv[4];
;         if (row < MP) row_load_bf16(X1B + (size_t)row * DM, nv, lane);
;         for (; row < MP; row += G * 8) {
;             f32x4 v[4];
; #pragma unroll
;             for (int j = 0; j < 4; ++j) v[j] = nv[j];
;             const int nr = row + G * 8;
;             if (nr < MP) row_load_bf16(X1B + (size_t)nr * DM, nv, lane);
;             const int b16 = row >> 12;
;             norm_apply(v, norm2_g, MOD + (size_t)b16 * 6144 + 4096, MOD + (size_t)b16 * 6144 + 3072, Hb + (size_t)row * DM, lane);
;         }
.Lp6_e0_go:
	v_lshlrev_b32_e32 v120, 16, v96
	v_and_b32_e32 v121, 0xffff0000, v96
	v_lshlrev_b32_e32 v122, 16, v97
	v_and_b32_e32 v123, 0xffff0000, v97
	v_lshlrev_b32_e32 v124, 16, v98
	v_and_b32_e32 v125, 0xffff0000, v98
	v_lshlrev_b32_e32 v126, 16, v99
	v_and_b32_e32 v127, 0xffff0000, v99
	v_lshlrev_b32_e32 v128, 16, v100
	v_and_b32_e32 v129, 0xffff0000, v100
	v_lshlrev_b32_e32 v130, 16, v101
	v_and_b32_e32 v131, 0xffff0000, v101
	v_lshlrev_b32_e32 v132, 16, v102
	v_and_b32_e32 v133, 0xffff0000, v102
	v_lshlrev_b32_e32 v134, 16, v103
	v_and_b32_e32 v135, 0xffff0000, v103
	s_add_i32 s22, s26, s88
	s_add_i32 s22, s22, s88
	s_min_i32 s22, s22, 0x7fff
	s_lshl_b32 s0, s22, 11
	s_add_u32 s0, s4, s0
	s_addc_u32 s1, s5, 0
	global_load_dwordx4 v[96:99], v0, s[0:1] nt
	global_load_dwordx4 v[100:103], v0, s[0:1] offset:1024 nt
	v_mul_f32_e32 v11, v120, v120
	v_mul_f32_e32 v12, v121, v121
	v_fmac_f32_e32 v11, v122, v122
	v_fmac_f32_e32 v12, v123, v123
	v_fmac_f32_e32 v11, v124, v124
	v_fmac_f32_e32 v12, v125, v125
	v_fmac_f32_e32 v11, v126, v126
	v_fmac_f32_e32 v12, v127, v127
	v_fmac_f32_e32 v11, v128, v128
	v_fmac_f32_e32 v12, v129, v129
	v_fmac_f32_e32 v11, v130, v130
	v_fmac_f32_e32 v12, v131, v131
	v_fmac_f32_e32 v11, v132, v132
	v_fmac_f32_e32 v12, v133, v133
	v_fmac_f32_e32 v11, v134, v134
	v_fmac_f32_e32 v12, v135, v135
	v_add_f32_e32 v11, v11, v12
	ds_bpermute_b32 v12, v2, v11
	s_waitcnt lgkmcnt(0)
	v_add_f32_e32 v11, v11, v12
	ds_bpermute_b32 v12, v3, v11
	s_waitcnt lgkmcnt(0)
	v_add_f32_e32 v11, v11, v12
	ds_bpermute_b32 v12, v5, v11
	s_waitcnt lgkmcnt(0)
	v_add_f32_e32 v11, v11, v12
	ds_bpermute_b32 v12, v7, v11
	s_waitcnt lgkmcnt(0)
	v_add_f32_e32 v11, v11, v12
	ds_bpermute_b32 v12, v8, v11
	s_waitcnt lgkmcnt(0)
	v_add_f32_e32 v11, v11, v12
	ds_bpermute_b32 v12, v9, v11
	s_waitcnt lgkmcnt(0)
	v_add_f32_e32 v11, v11, v12
	v_mov_b32_e32 v12, 0x358637bd
	v_fmac_f32_e32 v12, 0x3a800000, v11
	v_rsq_f32_e32 v13, v12
	s_nop 0
	s_lshl_b32 s12, s26, 11
	s_add_u32 s12, s30, s12
	s_addc_u32 s13, s31, 0
	s_add_u32 s12, s12, 0x1d00000
	s_addc_u32 s13, s13, 0
	v_mul_f32_e32 v120, v13, v120
	v_mul_f32_e32 v121, v13, v121
	v_mul_f32_e32 v122, v13, v122
	v_mul_f32_e32 v123, v13, v123
	v_mul_f32_e32 v124, v13, v124
	v_mul_f32_e32 v125, v13, v125
	v_mul_f32_e32 v126, v13, v126
	v_mul_f32_e32 v127, v13, v127
	v_mul_f32_e32 v128, v13, v128
	v_mul_f32_e32 v129, v13, v129
	v_mul_f32_e32 v130, v13, v130
	v_mul_f32_e32 v131, v13, v131
	v_mul_f32_e32 v132, v13, v132
	v_mul_f32_e32 v133, v13, v133
	v_mul_f32_e32 v134, v13, v134
	v_mul_f32_e32 v135, v13, v135
	v_mul_f32_e32 v120, v16, v120
	v_mul_f32_e32 v121, v17, v121
	v_mul_f32_e32 v122, v18, v122
	v_mul_f32_e32 v123, v19, v123
	v_mul_f32_e32 v124, v20, v124
	v_mul_f32_e32 v125, v21, v125
	v_mul_f32_e32 v126, v22, v126
	v_mul_f32_e32 v127, v23, v127
	v_mul_f32_e32 v128, v24, v128
	v_mul_f32_e32 v129, v25, v129
	v_mul_f32_e32 v130, v26, v130
	v_mul_f32_e32 v131, v27, v131
	v_mul_f32_e32 v132, v28, v132
	v_mul_f32_e32 v133, v29, v133
	v_mul_f32_e32 v134, v30, v134
	v_mul_f32_e32 v135, v31, v135
	v_add_f32_e32 v32, 1.0, v32
	v_add_f32_e32 v33, 1.0, v33
	v_add_f32_e32 v34, 1.0, v34
	v_add_f32_e32 v35, 1.0, v35
	v_add_f32_e32 v36, 1.0, v36
	v_add_f32_e32 v37, 1.0, v37
	v_add_f32_e32 v38, 1.0, v38
	v_add_f32_e32 v39, 1.0, v39
	v_add_f32_e32 v40, 1.0, v40
	v_add_f32_e32 v41, 1.0, v41
	v_add_f32_e32 v42, 1.0, v42
	v_add_f32_e32 v43, 1.0, v43
	v_add_f32_e32 v44, 1.0, v44
	v_add_f32_e32 v45, 1.0, v45
	v_add_f32_e32 v46, 1.0, v46
	v_add_f32_e32 v47, 1.0, v47
	v_fma_f32 v120, v32, v120, v48
	v_fma_f32 v121, v33, v121, v49
	v_fma_f32 v122, v34, v122, v50
	v_fma_f32 v123, v35, v123, v51
	v_fma_f32 v124, v36, v124, v52
	v_fma_f32 v125, v37, v125, v53
	v_fma_f32 v126, v38, v126, v54
	v_fma_f32 v127, v39, v127, v55
	v_fma_f32 v128, v40, v128, v56
	v_fma_f32 v129, v41, v129, v57
	v_fma_f32 v130, v42, v130, v58
	v_fma_f32 v131, v43, v131, v59
	v_fma_f32 v132, v44, v132, v60
	v_fma_f32 v133, v45, v133, v61
	v_fma_f32 v134, v46, v134, v62
	v_fma_f32 v135, v47, v135, v63
	v_cvt_pk_bf16_f32 v120, v120, v121
	v_cvt_pk_bf16_f32 v121, v122, v123
	v_cvt_pk_bf16_f32 v122, v124, v125
	v_cvt_pk_bf16_f32 v123, v126, v127
	v_cvt_pk_bf16_f32 v124, v128, v129
	v_cvt_pk_bf16_f32 v125, v130, v131
	v_cvt_pk_bf16_f32 v126, v132, v133
	v_cvt_pk_bf16_f32 v127, v134, v135
	global_store_dwordx4 v0, v[120:123], s[12:13] sc0 sc1
	global_store_dwordx4 v0, v[124:127], s[12:13] offset:1024 sc0 sc1
	s_add_i32 s26, s26, s88
	s_cmpk_gt_i32 s26, 0x7fff
	s_cbranch_scc1 .Lp6_done

; __device__ __forceinline__ unsigned cvt_pk_bf16(float lo, float hi) { unsigned r; asm("v_cvt_pk_bf16_f32 %0, %1, %2" : "=v"(r) : "v"(lo), "v"(hi)); return r; }
; #define FRESH_IDS() const int tid = fresh_tid(), lane = tid & 63, wid = __builtin_amdgcn_readfirstlane(tid >> 6); (void)tid; (void)lane; (void)wid
; __device__ __forceinline__ void norm_load(const float* xrow, f32x4 (&v)[4], int lane) {
; #pragma unroll
;     for (int j = 0; j < 4; ++j) v[j] = __builtin_nontemporal_load((const f32x4*)xrow + lane + 64 * j);
; }
; __device__ __forceinline__ void norm_apply(const f32x4 (&v)[4], const float* g, const float* sc, const float* sh, bf16_t* orow, int lane) {
;     float s = 0.f;
; #pragma unroll
;     for (int j = 0; j < 4; ++j) s += (v[j][0] * v[j][0] + v[j][1] * v[j][1]) + (v[j][2] * v[j][2] + v[j][3] * v[j][3]);
;     const float rstd = rsqrtf(wave_sum(s) * (1.f / 1024.f) + EPS);
; #pragma unroll
;     for (int j = 0; j < 4; ++j) { const int c4 = lane + 64 * j;
;         const f32x4 gg = *((const f32x4*)g + c4), cc = *((const f32x4*)sc + c4), hh = *((const f32x4*)sh + c4);
;         const f32x4 h = v[j] * rstd * gg * (cc + 1.f) + hh;
;         u32x2 w; w.x = cvt_pk_bf16(h[0], h[1]); w.y = cvt_pk_bf16(h[2], h[3]);
;         *((u32x2*)orow + c4) = w; }
; }
; __global__ void __launch_bounds__(512, 2) mega_fwd(Args a) {
;     ...
;     { FRESH_IDS();
;         int row = bx * 8 + wid; f32x4 nv[4];
;         if (row < MP) row_load_bf16(X1B + (size_t)row * DM, nv, lane);
;         for (; row < MP; row += G * 8) {
;             f32x4 v[4];
; #pragma unroll
;             for (int j = 0; j < 4; ++j) v[j] = nv[j];
;             const int nr = row + G * 8;
;             if (nr < MP) row_load_bf16(X1B + (size_t)nr * DM, nv, lane);
;             const int b16 = row >> 12;
;             norm_apply(v, norm2_g, MOD + (size_t)b16 * 6144 + 4096, MOD + (size_t)b16 * 6144 + 3072, Hb + (size_t)row * DM, lane);
;         }
.Lp6_o0_go:
	v_lshlrev_b32_e32 v120, 16, v104
	v_and_b32_e32 v121, 0xffff0000, v104
	v_lshlrev_b32_e32 v122, 16, v105
	v_and_b32_e32 v123, 0xffff0000, v105
	v_lshlrev_b32_e32 v124, 16, v106
	v_and_b32_e32 v125, 0xffff0000, v106
	v_lshlrev_b32_e32 v126, 16, v107
	v_and_b32_e32 v127, 0xffff0000, v107
	v_lshlrev_b32_e32 v128, 16, v108
	v_and_b32_e32 v129, 0xffff0000, v108
	v_lshlrev_b32_e32 v130, 16, v109
	v_and_b32_e32 v131, 0xffff0000, v109
	v_lshlrev_b32_e32 v132, 16, v110
	v_and_b32_e32 v133, 0xffff0000, v110
	v_lshlrev_b32_e32 v134, 16, v111
	v_and_b32_e32 v135, 0xffff0000, v111
	s_add_i32 s22, s26, s88
	s_add_i32 s22, s22, s88
	s_min_i32 s22, s22, 0x7fff
	s_lshl_b32 s0, s22, 11
	s_add_u32 s0, s4, s0
	s_addc_u32 s1, s5, 0
	global_load_dwordx4 v[104:107], v0, s[0:1] nt
	global_load_dwordx4 v[108:111], v0, s[0:1] offset:1024 nt
	v_mul_f32_e32 v11, v120, v120
	v_mul_f32_e32 v12, v121, v121
	v_fmac_f32_e32 v11, v122, v122
	v_fmac_f32_e32 v12, v123, v123
	v_fmac_f32_e32 v11, v124, v124
	v_fmac_f32_e32 v12, v125, v125
	v_fmac_f32_e32 v11, v126, v126
	v_fmac_f32_e32 v12, v127, v127
	v_fmac_f32_e32 v11, v128, v128
	v_fmac_f32_e32 v12, v129, v129
	v_fmac_f32_e32 v11, v130, v130
	v_fmac_f32_e32 v12, v131, v131
	v_fmac_f32_e32 v11, v132, v132
	v_fmac_f32_e32 v12, v133, v133
	v_fmac_f32_e32 v11, v134, v134
	v_fmac_f32_e32 v12, v135, v135
	v_add_f32_e32 v11, v11, v12
	ds_bpermute_b32 v12, v2, v11
	s_waitcnt lgkmcnt(0)
	v_add_f32_e32 v11, v11, v12
	ds_bpermute_b32 v12, v3, v11
	s_waitcnt lgkmcnt(0)
	v_add_f32_e32 v11, v11, v12
	ds_bpermute_b32 v12, v5, v11
	s_waitcnt lgkmcnt(0)
	v_add_f32_e32 v11, v11, v12
	ds_bpermute_b32 v12, v7, v11
	s_waitcnt lgkmcnt(0)
	v_add_f32_e32 v11, v11, v12
	ds_bpermute_b32 v12, v8, v11
	s_waitcnt lgkmcnt(0)
	v_add_f32_e32 v11, v11, v12
	ds_bpermute_b32 v12, v9, v11
	s_waitcnt lgkmcnt(0)
	v_add_f32_e32 v11, v11, v12
	v_mov_b32_e32 v12, 0x358637bd
	v_fmac_f32_e32 v12, 0x3a800000, v11
	v_rsq_f32_e32 v13, v12
	s_nop 0
	s_lshl_b32 s12, s26, 11
	s_add_u32 s12, s30, s12
	s_addc_u32 s13, s31, 0
	s_add_u32 s12, s12, 0x1d00000
	s_addc_u32 s13, s13, 0
	v_mul_f32_e32 v120, v13, v120
	v_mul_f32_e32 v121, v13, v121
	v_mul_f32_e32 v122, v13, v122
	v_mul_f32_e32 v123, v13, v123
	v_mul_f32_e32 v124, v13, v124
	v_mul_f32_e32 v125, v13, v125
	v_mul_f32_e32 v126, v13, v126
	v_mul_f32_e32 v127, v13, v127
	v_mul_f32_e32 v128, v13, v128
	v_mul_f32_e32 v129, v13, v129
	v_mul_f32_e32 v130, v13, v130
	v_mul_f32_e32 v131, v13, v131
	v_mul_f32_e32 v132, v13, v132
	v_mul_f32_e32 v133, v13, v133
	v_mul_f32_e32 v134, v13, v134
	v_mul_f32_e32 v135, v13, v135
	v_mul_f32_e32 v120, v16, v120
	v_mul_f32_e32 v121, v17, v121
	v_mul_f32_e32 v122, v18, v122
	v_mul_f32_e32 v123, v19, v123
	v_mul_f32_e32 v124, v20, v124
	v_mul_f32_e32 v125, v21, v125
	v_mul_f32_e32 v126, v22, v126
	v_mul_f32_e32 v127, v23, v127
	v_mul_f32_e32 v128, v24, v128
	v_mul_f32_e32 v129, v25, v129
	v_mul_f32_e32 v130, v26, v130
	v_mul_f32_e32 v131, v27, v131
	v_mul_f32_e32 v132, v28, v132
	v_mul_f32_e32 v133, v29, v133
	v_mul_f32_e32 v134, v30, v134
	v_mul_f32_e32 v135, v31, v135
	v_fma_f32 v120, v32, v120, v48
	v_fma_f32 v121, v33, v121, v49
	v_fma_f32 v122, v34, v122, v50
	v_fma_f32 v123, v35, v123, v51
	v_fma_f32 v124, v36, v124, v52
	v_fma_f32 v125, v37, v125, v53
	v_fma_f32 v126, v38, v126, v54
	v_fma_f32 v127, v39, v127, v55
	v_fma_f32 v128, v40, v128, v56
	v_fma_f32 v129, v41, v129, v57
	v_fma_f32 v130, v42, v130, v58
	v_fma_f32 v131, v43, v131, v59
	v_fma_f32 v132, v44, v132, v60
	v_fma_f32 v133, v45, v133, v61
	v_fma_f32 v134, v46, v134, v62
	v_fma_f32 v135, v47, v135, v63
	v_cvt_pk_bf16_f32 v120, v120, v121
	v_cvt_pk_bf16_f32 v121, v122, v123
	v_cvt_pk_bf16_f32 v122, v124, v125
	v_cvt_pk_bf16_f32 v123, v126, v127
	v_cvt_pk_bf16_f32 v124, v128, v129
	v_cvt_pk_bf16_f32 v125, v130, v131
	v_cvt_pk_bf16_f32 v126, v132, v133
	v_cvt_pk_bf16_f32 v127, v134, v135
	global_store_dwordx4 v0, v[120:123], s[12:13] sc0 sc1
	global_store_dwordx4 v0, v[124:127], s[12:13] offset:1024 sc0 sc1
	s_add_i32 s26, s26, s88
	s_cmpk_gt_i32 s26, 0x7fff
	s_cbranch_scc1 .Lp6_done

; __device__ __forceinline__ unsigned cvt_pk_bf16(float lo, float hi) { unsigned r; asm("v_cvt_pk_bf16_f32 %0, %1, %2" : "=v"(r) : "v"(lo), "v"(hi)); return r; }
; #define FRESH_IDS() const int tid = fresh_tid(), lane = tid & 63, wid = __builtin_amdgcn_readfirstlane(tid >> 6); (void)tid; (void)lane; (void)wid
; __device__ __forceinline__ void norm_load(const float* xrow, f32x4 (&v)[4], int lane) {
; #pragma unroll
;     for (int j = 0; j < 4; ++j) v[j] = __builtin_nontemporal_load((const f32x4*)xrow + lane + 64 * j);
; }
; __device__ __forceinline__ void norm_apply(const f32x4 (&v)[4], const float* g, const float* sc, const float* sh, bf16_t* orow, int lane) {
;     float s = 0.f;
; #pragma unroll
;     for (int j = 0; j < 4; ++j) s += (v[j][0] * v[j][0] + v[j][1] * v[j][1]) + (v[j][2] * v[j][2] + v[j][3] * v[j][3]);
;     const float rstd = rsqrtf(wave_sum(s) * (1.f / 1024.f) + EPS);
; #pragma unroll
;     for (int j = 0; j < 4; ++j) { const int c4 = lane + 64 * j;
;         const f32x4 gg = *((const f32x4*)g + c4), cc = *((const f32x4*)sc + c4), hh = *((const f32x4*)sh + c4);
;         const f32x4 h = v[j] * rstd * gg * (cc + 1.f) + hh;
;         u32x2 w; w.x = cvt_pk_bf16(h[0], h[1]); w.y = cvt_pk_bf16(h[2], h[3]);
;         *((u32x2*)orow + c4) = w; }
; }
; __global__ void __launch_bounds__(512, 2) mega_fwd(Args a) {
;     ...
;     { FRESH_IDS();
;         int row = bx * 8 + wid; f32x4 nv[4];
;         if (row < MP) row_load_bf16(X1B + (size_t)row * DM, nv, lane);
;         for (; row < MP; row += G * 8) {
;             f32x4 v[4];
; #pragma unroll
;             for (int j = 0; j < 4; ++j) v[j] = nv[j];
;             const int nr = row + G * 8;
;             if (nr < MP) row_load_bf16(X1B + (size_t)nr * DM, nv, lane);
;             const int b16 = row >> 12;
;             norm_apply(v, norm2_g, MOD + (size_t)b16 * 6144 + 4096, MOD + (size_t)b16 * 6144 + 3072, Hb + (size_t)row * DM, lane);
;         }
.Lp6_e1_go:
	v_lshlrev_b32_e32 v120, 16, v96
	v_and_b32_e32 v121, 0xffff0000, v96
	v_lshlrev_b32_e32 v122, 16, v97
	v_and_b32_e32 v123, 0xffff0000, v97
	v_lshlrev_b32_e32 v124, 16, v98
	v_and_b32_e32 v125, 0xffff0000, v98
	v_lshlrev_b32_e32 v126, 16, v99
	v_and_b32_e32 v127, 0xffff0000, v99
	v_lshlrev_b32_e32 v128, 16, v100
	v_and_b32_e32 v129, 0xffff0000, v100
	v_lshlrev_b32_e32 v130, 16, v101
	v_and_b32_e32 v131, 0xffff0000, v101
	v_lshlrev_b32_e32 v132, 16, v102
	v_and_b32_e32 v133, 0xffff0000, v102
	v_lshlrev_b32_e32 v134, 16, v103
	v_and_b32_e32 v135, 0xffff0000, v103
	s_add_i32 s22, s26, s88
	s_add_i32 s22, s22, s88
	s_min_i32 s22, s22, 0x7fff
	s_lshl_b32 s0, s22, 11
	s_add_u32 s0, s4, s0
	s_addc_u32 s1, s5, 0
	global_load_dwordx4 v[96:99], v0, s[0:1] nt
	global_load_dwordx4 v[100:103], v0, s[0:1] offset:1024 nt
	v_mul_f32_e32 v11, v120, v120
	v_mul_f32_e32 v12, v121, v121
	v_fmac_f32_e32 v11, v122, v122
	v_fmac_f32_e32 v12, v123, v123
	v_fmac_f32_e32 v11, v124, v124
	v_fmac_f32_e32 v12, v125, v125
	v_fmac_f32_e32 v11, v126, v126
	v_fmac_f32_e32 v12, v127, v127
	v_fmac_f32_e32 v11, v128, v128
	v_fmac_f32_e32 v12, v129, v129
	v_fmac_f32_e32 v11, v130, v130
	v_fmac_f32_e32 v12, v131, v131
	v_fmac_f32_e32 v11, v132, v132
	v_fmac_f32_e32 v12, v133, v133
	v_fmac_f32_e32 v11, v134, v134
	v_fmac_f32_e32 v12, v135, v135
	v_add_f32_e32 v11, v11, v12
	ds_bpermute_b32 v12, v2, v11
	s_waitcnt lgkmcnt(0)
	v_add_f32_e32 v11, v11, v12
	ds_bpermute_b32 v12, v3, v11
	s_waitcnt lgkmcnt(0)
	v_add_f32_e32 v11, v11, v12
	ds_bpermute_b32 v12, v5, v11
	s_waitcnt lgkmcnt(0)
	v_add_f32_e32 v11, v11, v12
	ds_bpermute_b32 v12, v7, v11
	s_waitcnt lgkmcnt(0)
	v_add_f32_e32 v11, v11, v12
	ds_bpermute_b32 v12, v8, v11
	s_waitcnt lgkmcnt(0)
	v_add_f32_e32 v11, v11, v12
	ds_bpermute_b32 v12, v9, v11
	s_waitcnt lgkmcnt(0)
	v_add_f32_e32 v11, v11, v12
	v_mov_b32_e32 v12, 0x358637bd
	v_fmac_f32_e32 v12, 0x3a800000, v11
	v_rsq_f32_e32 v13, v12
	s_nop 0
	s_lshl_b32 s12, s26, 11
	s_add_u32 s12, s30, s12
	s_addc_u32 s13, s31, 0
	s_add_u32 s12, s12, 0x1d00000
	s_addc_u32 s13, s13, 0
	v_mul_f32_e32 v120, v13, v120
	v_mul_f32_e32 v121, v13, v121
	v_mul_f32_e32 v122, v13, v122
	v_mul_f32_e32 v123, v13, v123
	v_mul_f32_e32 v124, v13, v124
	v_mul_f32_e32 v125, v13, v125
	v_mul_f32_e32 v126, v13, v126
	v_mul_f32_e32 v127, v13, v127
	v_mul_f32_e32 v128, v13, v128
	v_mul_f32_e32 v129, v13, v129
	v_mul_f32_e32 v130, v13, v130
	v_mul_f32_e32 v131, v13, v131
	v_mul_f32_e32 v132, v13, v132
	v_mul_f32_e32 v133, v13, v133
	v_mul_f32_e32 v134, v13, v134
	v_mul_f32_e32 v135, v13, v135
	v_mul_f32_e32 v120, v16, v120
	v_mul_f32_e32 v121, v17, v121
	v_mul_f32_e32 v122, v18, v122
	v_mul_f32_e32 v123, v19, v123
	v_mul_f32_e32 v124, v20, v124
	v_mul_f32_e32 v125, v21, v125
	v_mul_f32_e32 v126, v22, v126
	v_mul_f32_e32 v127, v23, v127
	v_mul_f32_e32 v128, v24, v128
	v_mul_f32_e32 v129, v25, v129
	v_mul_f32_e32 v130, v26, v130
	v_mul_f32_e32 v131, v27, v131
	v_mul_f32_e32 v132, v28, v132
	v_mul_f32_e32 v133, v29, v133
	v_mul_f32_e32 v134, v30, v134
	v_mul_f32_e32 v135, v31, v135
	v_add_f32_e32 v64, 1.0, v64
	v_add_f32_e32 v65, 1.0, v65
	v_add_f32_e32 v66, 1.0, v66
	v_add_f32_e32 v67, 1.0, v67
	v_add_f32_e32 v68, 1.0, v68
	v_add_f32_e32 v69, 1.0, v69
	v_add_f32_e32 v70, 1.0, v70
	v_add_f32_e32 v71, 1.0, v71
	v_add_f32_e32 v72, 1.0, v72
	v_add_f32_e32 v73, 1.0, v73
	v_add_f32_e32 v74, 1.0, v74
	v_add_f32_e32 v75, 1.0, v75
	v_add_f32_e32 v76, 1.0, v76
	v_add_f32_e32 v77, 1.0, v77
	v_add_f32_e32 v78, 1.0, v78
	v_add_f32_e32 v79, 1.0, v79
	v_fma_f32 v120, v64, v120, v80
	v_fma_f32 v121, v65, v121, v81
	v_fma_f32 v122, v66, v122, v82
	v_fma_f32 v123, v67, v123, v83
	v_fma_f32 v124, v68, v124, v84
	v_fma_f32 v125, v69, v125, v85
	v_fma_f32 v126, v70, v126, v86
	v_fma_f32 v127, v71, v127, v87
	v_fma_f32 v128, v72, v128, v88
	v_fma_f32 v129, v73, v129, v89
	v_fma_f32 v130, v74, v130, v90
	v_fma_f32 v131, v75, v131, v91
	v_fma_f32 v132, v76, v132, v92
	v_fma_f32 v133, v77, v133, v93
	v_fma_f32 v134, v78, v134, v94
	v_fma_f32 v135, v79, v135, v95
	v_cvt_pk_bf16_f32 v120, v120, v121
	v_cvt_pk_bf16_f32 v121, v122, v123
	v_cvt_pk_bf16_f32 v122, v124, v125
	v_cvt_pk_bf16_f32 v123, v126, v127
	v_cvt_pk_bf16_f32 v124, v128, v129
	v_cvt_pk_bf16_f32 v125, v130, v131
	v_cvt_pk_bf16_f32 v126, v132, v133
	v_cvt_pk_bf16_f32 v127, v134, v135
	global_store_dwordx4 v0, v[120:123], s[12:13] sc0 sc1
	global_store_dwordx4 v0, v[124:127], s[12:13] offset:1024 sc0 sc1
	s_add_i32 s26, s26, s88
	s_cmpk_gt_i32 s26, 0x7fff
	s_cbranch_scc1 .Lp6_done

; __device__ __forceinline__ unsigned cvt_pk_bf16(float lo, float hi) { unsigned r; asm("v_cvt_pk_bf16_f32 %0, %1, %2" : "=v"(r) : "v"(lo), "v"(hi)); return r; }
; #define FRESH_IDS() const int tid = fresh_tid(), lane = tid & 63, wid = __builtin_amdgcn_readfirstlane(tid >> 6); (void)tid; (void)lane; (void)wid
; __device__ __forceinline__ void norm_load(const float* xrow, f32x4 (&v)[4], int lane) {
; #pragma unroll
;     for (int j = 0; j < 4; ++j) v[j] = __builtin_nontemporal_load((const f32x4*)xrow + lane + 64 * j);
; }
; __device__ __forceinline__ void norm_apply(const f32x4 (&v)[4], const float* g, const float* sc, const float* sh, bf16_t* orow, int lane) {
;     float s = 0.f;
; #pragma unroll
;     for (int j = 0; j < 4; ++j) s += (v[j][0] * v[j][0] + v[j][1] * v[j][1]) + (v[j][2] * v[j][2] + v[j][3] * v[j][3]);
;     const float rstd = rsqrtf(wave_sum(s) * (1.f / 1024.f) + EPS);
; #pragma unroll
;     for (int j = 0; j < 4; ++j) { const int c4 = lane + 64 * j;
;         const f32x4 gg = *((const f32x4*)g + c4), cc = *((const f32x4*)sc + c4), hh = *((const f32x4*)sh + c4);
;         const f32x4 h = v[j] * rstd * gg * (cc + 1.f) + hh;
;         u32x2 w; w.x = cvt_pk_bf16(h[0], h[1]); w.y = cvt_pk_bf16(h[2], h[3]);
;         *((u32x2*)orow + c4) = w; }
; }
; __global__ void __launch_bounds__(512, 2) mega_fwd(Args a) {
;     ...
;     { FRESH_IDS();
;         int row = bx * 8 + wid; f32x4 nv[4];
;         if (row < MP) row_load_bf16(X1B + (size_t)row * DM, nv, lane);
;         for (; row < MP; row += G * 8) {
;             f32x4 v[4];
; #pragma unroll
;             for (int j = 0; j < 4; ++j) v[j] = nv[j];
;             const int nr = row + G * 8;
;             if (nr < MP) row_load_bf16(X1B + (size_t)nr * DM, nv, lane);
;             const int b16 = row >> 12;
;             norm_apply(v, norm2_g, MOD + (size_t)b16 * 6144 + 4096, MOD + (size_t)b16 * 6144 + 3072, Hb + (size_t)row * DM, lane);
;         }
.Lp6_o1_go:
	v_lshlrev_b32_e32 v120, 16, v104
	v_and_b32_e32 v121, 0xffff0000, v104
	v_lshlrev_b32_e32 v122, 16, v105
	v_and_b32_e32 v123, 0xffff0000, v105
	v_lshlrev_b32_e32 v124, 16, v106
	v_and_b32_e32 v125, 0xffff0000, v106
	v_lshlrev_b32_e32 v126, 16, v107
	v_and_b32_e32 v127, 0xffff0000, v107
	v_lshlrev_b32_e32 v128, 16, v108
	v_and_b32_e32 v129, 0xffff0000, v108
	v_lshlrev_b32_e32 v130, 16, v109
	v_and_b32_e32 v131, 0xffff0000, v109
	v_lshlrev_b32_e32 v132, 16, v110
	v_and_b32_e32 v133, 0xffff0000, v110
	v_lshlrev_b32_e32 v134, 16, v111
	v_and_b32_e32 v135, 0xffff0000, v111
	s_add_i32 s22, s26, s88
	s_add_i32 s22, s22, s88
	s_min_i32 s22, s22, 0x7fff
	s_lshl_b32 s0, s22, 11
	s_add_u32 s0, s4, s0
	s_addc_u32 s1, s5, 0
	global_load_dwordx4 v[104:107], v0, s[0:1] nt
	global_load_dwordx4 v[108:111], v0, s[0:1] offset:1024 nt
	v_mul_f32_e32 v11, v120, v120
	v_mul_f32_e32 v12, v121, v121
	v_fmac_f32_e32 v11, v122, v122
	v_fmac_f32_e32 v12, v123, v123
	v_fmac_f32_e32 v11, v124, v124
	v_fmac_f32_e32 v12, v125, v125
	v_fmac_f32_e32 v11, v126, v126
	v_fmac_f32_e32 v12, v127, v127
	v_fmac_f32_e32 v11, v128, v128
	v_fmac_f32_e32 v12, v129, v129
	v_fmac_f32_e32 v11, v130, v130
	v_fmac_f32_e32 v12, v131, v131
	v_fmac_f32_e32 v11, v132, v132
	v_fmac_f32_e32 v12, v133, v133
	v_fmac_f32_e32 v11, v134, v134
	v_fmac_f32_e32 v12, v135, v135
	v_add_f32_e32 v11, v11, v12
	ds_bpermute_b32 v12, v2, v11
	s_waitcnt lgkmcnt(0)
	v_add_f32_e32 v11, v11, v12
	ds_bpermute_b32 v12, v3, v11
	s_waitcnt lgkmcnt(0)
	v_add_f32_e32 v11, v11, v12
	ds_bpermute_b32 v12, v5, v11
	s_waitcnt lgkmcnt(0)
	v_add_f32_e32 v11, v11, v12
	ds_bpermute_b32 v12, v7, v11
	s_waitcnt lgkmcnt(0)
	v_add_f32_e32 v11, v11, v12
	ds_bpermute_b32 v12, v8, v11
	s_waitcnt lgkmcnt(0)
	v_add_f32_e32 v11, v11, v12
	ds_bpermute_b32 v12, v9, v11
	s_waitcnt lgkmcnt(0)
	v_add_f32_e32 v11, v11, v12
	v_mov_b32_e32 v12, 0x358637bd
	v_fmac_f32_e32 v12, 0x3a800000, v11
	v_rsq_f32_e32 v13, v12
	s_nop 0
	s_lshl_b32 s12, s26, 11
	s_add_u32 s12, s30, s12
	s_addc_u32 s13, s31, 0
	s_add_u32 s12, s12, 0x1d00000
	s_addc_u32 s13, s13, 0
	v_mul_f32_e32 v120, v13, v120
	v_mul_f32_e32 v121, v13, v121
	v_mul_f32_e32 v122, v13, v122
	v_mul_f32_e32 v123, v13, v123
	v_mul_f32_e32 v124, v13, v124
	v_mul_f32_e32 v125, v13, v125
	v_mul_f32_e32 v126, v13, v126
	v_mul_f32_e32 v127, v13, v127
	v_mul_f32_e32 v128, v13, v128
	v_mul_f32_e32 v129, v13, v129
	v_mul_f32_e32 v130, v13, v130
	v_mul_f32_e32 v131, v13, v131
	v_mul_f32_e32 v132, v13, v132
	v_mul_f32_e32 v133, v13, v133
	v_mul_f32_e32 v134, v13, v134
	v_mul_f32_e32 v135, v13, v135
	v_mul_f32_e32 v120, v16, v120
	v_mul_f32_e32 v121, v17, v121
	v_mul_f32_e32 v122, v18, v122
	v_mul_f32_e32 v123, v19, v123
	v_mul_f32_e32 v124, v20, v124
	v_mul_f32_e32 v125, v21, v125
	v_mul_f32_e32 v126, v22, v126
	v_mul_f32_e32 v127, v23, v127
	v_mul_f32_e32 v128, v24, v128
	v_mul_f32_e32 v129, v25, v129
	v_mul_f32_e32 v130, v26, v130
	v_mul_f32_e32 v131, v27, v131
	v_mul_f32_e32 v132, v28, v132
	v_mul_f32_e32 v133, v29, v133
	v_mul_f32_e32 v134, v30, v134
	v_mul_f32_e32 v135, v31, v135
	v_fma_f32 v120, v64, v120, v80
	v_fma_f32 v121, v65, v121, v81
	v_fma_f32 v122, v66, v122, v82
	v_fma_f32 v123, v67, v123, v83
	v_fma_f32 v124, v68, v124, v84
	v_fma_f32 v125, v69, v125, v85
	v_fma_f32 v126, v70, v126, v86
	v_fma_f32 v127, v71, v127, v87
	v_fma_f32 v128, v72, v128, v88
	v_fma_f32 v129, v73, v129, v89
	v_fma_f32 v130, v74, v130, v90
	v_fma_f32 v131, v75, v131, v91
	v_fma_f32 v132, v76, v132, v92
	v_fma_f32 v133, v77, v133, v93
	v_fma_f32 v134, v78, v134, v94
	v_fma_f32 v135, v79, v135, v95
	v_cvt_pk_bf16_f32 v120, v120, v121
	v_cvt_pk_bf16_f32 v121, v122, v123
	v_cvt_pk_bf16_f32 v122, v124, v125
	v_cvt_pk_bf16_f32 v123, v126, v127
	v_cvt_pk_bf16_f32 v124, v128, v129
	v_cvt_pk_bf16_f32 v125, v130, v131
	v_cvt_pk_bf16_f32 v126, v132, v133
	v_cvt_pk_bf16_f32 v127, v134, v135
	global_store_dwordx4 v0, v[120:123], s[12:13] sc0 sc1
	global_store_dwordx4 v0, v[124:127], s[12:13] offset:1024 sc0 sc1
	s_add_i32 s26, s26, s88
	s_cmpk_gt_i32 s26, 0x7fff
	s_cbranch_scc1 .Lp6_done
	s_branch .Lp6_e0
